# v19
# speedup vs baseline: 1.0191x; 1.0085x over previous
.LBB0_414:
	v_readlane_b32 s0, v252, 31
	v_readlane_b32 s1, v252, 32
	v_readlane_b32 s80, v254, 35
	s_andn2_b64 vcc, exec, s[0:1]
	v_readlane_b32 s81, v254, 36
	v_readlane_b32 s82, v254, 37
	v_readlane_b32 s83, v254, 38
	v_readlane_b32 s84, v254, 39
	v_readlane_b32 s85, v254, 40
	v_readlane_b32 s86, v254, 41
	v_readlane_b32 s87, v254, 42
	v_readlane_b32 s88, v254, 43
	v_readlane_b32 s89, v254, 44
	v_readlane_b32 s90, v254, 45
	v_readlane_b32 s91, v254, 46
	v_readlane_b32 s92, v254, 47
	v_readlane_b32 s93, v254, 48
	v_readlane_b32 s94, v254, 49
	v_readlane_b32 s95, v254, 50
	s_cbranch_vccnz .LBB0_420
	v_readlane_b32 s0, v254, 23
	v_mov_b32_e32 v6, v167
	s_mov_b32 s26, 64
	v_mov_b32_e32 v0, s0
	ds_read_b32 v0, v0
	s_waitcnt lgkmcnt(0)
	v_readfirstlane_b32 s0, v0
	s_lshl_b32 s1, s0, 1
	s_ashr_i32 s9, s0, 6
	s_lshl_b32 s14, s0, 3
	s_bfe_u32 s17, s0, 0x30003
	s_and_b32 s0, s1, 12
	s_add_i32 s0, s0, s9
	s_and_b32 s1, s14, 8
	v_ashrrev_i32_e32 v7, 2, v6
	s_lshl_b32 s9, s0, 7
	s_or_b32 s1, s1, s17
	v_add_u32_e32 v0, s9, v7
	v_add_u32_e32 v0, 0x2000, v0
	s_lshl_b32 s1, s1, 7
	v_mad_i64_i32 v[2:3], s[38:39], v0, s6, 0
	v_add_u32_e32 v0, s1, v7
	v_mad_i64_i32 v[4:5], s[38:39], v0, s6, 0
	v_lshlrev_b32_e32 v0, 5, v6
	v_lshl_add_u64 v[4:5], v[4:5], 1, s[44:45]
	v_and_b32_e32 v0, 0x60, v0
	v_lshl_add_u64 v[2:3], v[2:3], 1, s[22:23]
	v_lshl_add_u64 v[52:53], v[4:5], 0, v[0:1]
	v_lshl_add_u64 v[50:51], v[2:3], 0, v[0:1]
	global_load_dwordx4 v[34:37], v[52:53], off offset:16
	global_load_dwordx4 v[38:41], v[52:53], off
	global_load_dwordx4 v[42:45], v[50:51], off offset:16
	global_load_dwordx4 v[46:49], v[50:51], off
	s_movk_i32 s6, 0xa0
	v_mul_lo_u32 v2, v7, s6
	v_add3_u32 v57, 0, v0, v2
	v_lshrrev_b32_e32 v0, 1, v6
	v_and_b32_e32 v55, 15, v6
	v_and_b32_e32 v56, 0xffffffc0, v7
	v_and_b32_e32 v0, 0x60, v0
	v_bfe_u32 v54, v6, 4, 2
	v_or_b32_e32 v2, v56, v55
	v_or_b32_e32 v4, v0, v55
	v_lshl_add_u32 v3, v54, 4, 0
	v_mul_lo_u32 v5, v2, s6
	v_mul_u32_u24_e32 v4, 0xa0, v4
	v_mov_b32_e32 v2, 0
	s_mov_b32 s6, 0
	v_add_u32_e32 v58, v3, v5
	v_add_u32_e32 v59, v3, v4
	v_mov_b32_e32 v3, v2
	v_mov_b32_e32 v4, v2
	v_mov_b32_e32 v5, v2
	v_mov_b32_e32 v18, v2
	v_mov_b32_e32 v19, v2
	v_mov_b32_e32 v20, v2
	v_mov_b32_e32 v21, v2
	v_mov_b32_e32 v6, v2
	v_mov_b32_e32 v7, v2
	v_mov_b32_e32 v8, v2
	v_mov_b32_e32 v9, v2
	v_mov_b32_e32 v22, v2
	v_mov_b32_e32 v23, v2
	v_mov_b32_e32 v24, v2
	v_mov_b32_e32 v25, v2
	v_mov_b32_e32 v10, v2
	v_mov_b32_e32 v11, v2
	v_mov_b32_e32 v12, v2
	v_mov_b32_e32 v13, v2
	v_mov_b32_e32 v26, v2
	v_mov_b32_e32 v27, v2
	v_mov_b32_e32 v28, v2
	v_mov_b32_e32 v29, v2
	v_mov_b32_e32 v14, v2
	v_mov_b32_e32 v15, v2
	v_mov_b32_e32 v16, v2
	v_mov_b32_e32 v17, v2
	v_mov_b32_e32 v30, v2
	v_mov_b32_e32 v31, v2
	v_mov_b32_e32 v32, v2
	v_mov_b32_e32 v33, v2
	s_branch .LBB0_417
.LBB0_417:
	s_mov_b32 s22, 0x80
	s_mov_b32 s23, 0
	v_lshl_add_u64 v[124:125], v[50:51], 0, s[22:23]
	v_lshl_add_u64 v[126:127], v[52:53], 0, s[22:23]
	global_load_dwordx4 v[84:87], v[124:125], off
	global_load_dwordx4 v[80:83], v[124:125], off offset:16
	global_load_dwordx4 v[76:79], v[126:127], off
	global_load_dwordx4 v[72:75], v[126:127], off offset:16
	s_waitcnt vmcnt(4) lgkmcnt(0)
	s_barrier
	ds_write_b128 v57, v[46:49]
	ds_write_b128 v57, v[42:45] offset:16
	ds_write_b128 v57, v[38:41] offset:20480
	ds_write_b128 v57, v[34:37] offset:20496
	s_waitcnt lgkmcnt(0)
	s_mov_b32 s22, 0x100
	v_lshl_add_u64 v[124:125], v[50:51], 0, s[22:23]
	v_lshl_add_u64 v[126:127], v[52:53], 0, s[22:23]
	global_load_dwordx4 v[46:49], v[124:125], off
	global_load_dwordx4 v[42:45], v[124:125], off offset:16
	global_load_dwordx4 v[38:41], v[126:127], off
	global_load_dwordx4 v[34:37], v[126:127], off offset:16
	s_barrier
	s_mov_b32 s6, 0
.Lsrt_loop:
	s_waitcnt vmcnt(4)
	ds_write_b128 v57, v[84:87] offset:40960
	ds_write_b128 v57, v[80:83] offset:40976
	ds_write_b128 v57, v[76:79] offset:61440
	ds_write_b128 v57, v[72:75] offset:61456
	ds_read_b128 v[60:63], v59 offset:20480
	ds_read_b128 v[64:67], v58
	ds_read_b128 v[68:71], v59 offset:23040
	ds_read_b128 v[88:91], v58 offset:2560
	ds_read_b128 v[92:95], v58 offset:5120
	ds_read_b128 v[96:99], v58 offset:7680
	ds_read_b128 v[100:103], v59 offset:20544
	ds_read_b128 v[104:107], v58 offset:64
	ds_read_b128 v[108:111], v59 offset:23104
	ds_read_b128 v[112:115], v58 offset:2624
	ds_read_b128 v[116:119], v58 offset:5184
	ds_read_b128 v[120:123], v58 offset:7744
	s_add_i32 s14, s6, 3
	s_add_i32 s22, s64, -1
	s_min_u32 s14, s14, s22
	s_lshl_b32 s22, s14, 7
	s_waitcnt lgkmcnt(12)
	v_lshl_add_u64 v[124:125], v[50:51], 0, s[22:23]
	v_lshl_add_u64 v[126:127], v[52:53], 0, s[22:23]
	global_load_dwordx4 v[84:87], v[124:125], off
	global_load_dwordx4 v[80:83], v[124:125], off offset:16
	global_load_dwordx4 v[76:79], v[126:127], off
	global_load_dwordx4 v[72:75], v[126:127], off offset:16
	s_waitcnt lgkmcnt(10)
	v_mfma_f32_16x16x32_bf16 v[30:33], v[60:63], v[64:67], v[30:33]
	s_waitcnt lgkmcnt(9)
	v_mfma_f32_16x16x32_bf16 v[14:17], v[68:71], v[64:67], v[14:17]
	s_waitcnt lgkmcnt(8)
	v_mfma_f32_16x16x32_bf16 v[26:29], v[60:63], v[88:91], v[26:29]
	v_mfma_f32_16x16x32_bf16 v[10:13], v[68:71], v[88:91], v[10:13]
	s_waitcnt lgkmcnt(7)
	v_mfma_f32_16x16x32_bf16 v[22:25], v[60:63], v[92:95], v[22:25]
	v_mfma_f32_16x16x32_bf16 v[6:9], v[68:71], v[92:95], v[6:9]
	s_waitcnt lgkmcnt(6)
	v_mfma_f32_16x16x32_bf16 v[18:21], v[60:63], v[96:99], v[18:21]
	v_mfma_f32_16x16x32_bf16 v[2:5], v[68:71], v[96:99], v[2:5]
	s_waitcnt lgkmcnt(4)
	v_mfma_f32_16x16x32_bf16 v[30:33], v[100:103], v[104:107], v[30:33]
	s_waitcnt lgkmcnt(3)
	v_mfma_f32_16x16x32_bf16 v[14:17], v[108:111], v[104:107], v[14:17]
	s_waitcnt lgkmcnt(2)
	v_mfma_f32_16x16x32_bf16 v[26:29], v[100:103], v[112:115], v[26:29]
	v_mfma_f32_16x16x32_bf16 v[10:13], v[108:111], v[112:115], v[10:13]
	s_waitcnt lgkmcnt(1)
	v_mfma_f32_16x16x32_bf16 v[22:25], v[100:103], v[116:119], v[22:25]
	v_mfma_f32_16x16x32_bf16 v[6:9], v[108:111], v[116:119], v[6:9]
	s_waitcnt lgkmcnt(0)
	v_mfma_f32_16x16x32_bf16 v[18:21], v[100:103], v[120:123], v[18:21]
	v_mfma_f32_16x16x32_bf16 v[2:5], v[108:111], v[120:123], v[2:5]
	s_barrier
	s_waitcnt vmcnt(4)
	ds_write_b128 v57, v[46:49]
	ds_write_b128 v57, v[42:45] offset:16
	ds_write_b128 v57, v[38:41] offset:20480
	ds_write_b128 v57, v[34:37] offset:20496
	ds_read_b128 v[60:63], v59 offset:61440
	ds_read_b128 v[64:67], v58 offset:40960
	ds_read_b128 v[68:71], v59 offset:64000
	ds_read_b128 v[88:91], v58 offset:43520
	ds_read_b128 v[92:95], v58 offset:46080
	ds_read_b128 v[96:99], v58 offset:48640
	ds_read_b128 v[100:103], v59 offset:61504
	ds_read_b128 v[104:107], v58 offset:41024
	ds_read_b128 v[108:111], v59 offset:64064
	ds_read_b128 v[112:115], v58 offset:43584
	ds_read_b128 v[116:119], v58 offset:46144
	ds_read_b128 v[120:123], v58 offset:48704
	s_add_i32 s14, s6, 4
	s_add_i32 s22, s64, -1
	s_min_u32 s14, s14, s22
	s_lshl_b32 s22, s14, 7
	s_waitcnt lgkmcnt(12)
	v_lshl_add_u64 v[124:125], v[50:51], 0, s[22:23]
	v_lshl_add_u64 v[126:127], v[52:53], 0, s[22:23]
	global_load_dwordx4 v[46:49], v[124:125], off
	global_load_dwordx4 v[42:45], v[124:125], off offset:16
	global_load_dwordx4 v[38:41], v[126:127], off
	global_load_dwordx4 v[34:37], v[126:127], off offset:16
	s_waitcnt lgkmcnt(10)
	v_mfma_f32_16x16x32_bf16 v[30:33], v[60:63], v[64:67], v[30:33]
	s_waitcnt lgkmcnt(9)
	v_mfma_f32_16x16x32_bf16 v[14:17], v[68:71], v[64:67], v[14:17]
	s_waitcnt lgkmcnt(8)
	v_mfma_f32_16x16x32_bf16 v[26:29], v[60:63], v[88:91], v[26:29]
	v_mfma_f32_16x16x32_bf16 v[10:13], v[68:71], v[88:91], v[10:13]
	s_waitcnt lgkmcnt(7)
	v_mfma_f32_16x16x32_bf16 v[22:25], v[60:63], v[92:95], v[22:25]
	v_mfma_f32_16x16x32_bf16 v[6:9], v[68:71], v[92:95], v[6:9]
	s_waitcnt lgkmcnt(6)
	v_mfma_f32_16x16x32_bf16 v[18:21], v[60:63], v[96:99], v[18:21]
	v_mfma_f32_16x16x32_bf16 v[2:5], v[68:71], v[96:99], v[2:5]
	s_waitcnt lgkmcnt(4)
	v_mfma_f32_16x16x32_bf16 v[30:33], v[100:103], v[104:107], v[30:33]
	s_waitcnt lgkmcnt(3)
	v_mfma_f32_16x16x32_bf16 v[14:17], v[108:111], v[104:107], v[14:17]
	s_waitcnt lgkmcnt(2)
	v_mfma_f32_16x16x32_bf16 v[26:29], v[100:103], v[112:115], v[26:29]
	v_mfma_f32_16x16x32_bf16 v[10:13], v[108:111], v[112:115], v[10:13]
	s_waitcnt lgkmcnt(1)
	v_mfma_f32_16x16x32_bf16 v[22:25], v[100:103], v[116:119], v[22:25]
	v_mfma_f32_16x16x32_bf16 v[6:9], v[108:111], v[116:119], v[6:9]
	s_waitcnt lgkmcnt(0)
	v_mfma_f32_16x16x32_bf16 v[18:21], v[100:103], v[120:123], v[18:21]
	v_mfma_f32_16x16x32_bf16 v[2:5], v[108:111], v[120:123], v[2:5]
	s_barrier
	s_add_i32 s6, s6, 2
	s_cmp_lt_u32 s6, s64
	s_cbranch_scc1 .Lsrt_loop
	s_waitcnt vmcnt(0)
